# last two KV tiles of each attention item run as two more pipelined half-trips from the loop generator instead of the compiler's serial tail
# speedup vs baseline: 1.0040x; 1.0003x over previous
; DI void attn_item(const P& p, int l, int item, char* smem) {
;     ...
;   for (int kt = -1; kt < 128; ++kt) {
;     if (kt + 1 < 128) {
;       u16* Kd = Ks + ((kt + 1) & 1) * (256 * 72);
;       u16* Vd = Kd + 2 * 64 * 72;
; #pragma unroll
;       for (int i = 0; i < 2; ++i) {
;         const int row = tid >> 3, kc = tid & 7;
;         *(u32x4*)(Kd + (i * 64 + row) * 72 + kc * 8) = kreg[i];
;       }
; #pragma unroll
;       for (int i = 0; i < 2; ++i) {
;         const int cid = tid + NT * i;
;         const int e = cid >> 3, kc = cid & 7;
;         uint2 w0; w0.x = vreg[i][0]; w0.y = vreg[i][1];
;         uint2 w1; w1.x = vreg[i][2]; w1.y = vreg[i][3];
;         u16* vd = Vd + e * 72 + (kc >> 1) * 16 + (kc & 1) * 4;
;         *(uint2*)vd = w0;
;         *(uint2*)(vd + 8) = w1;
;       }
;     }
;     if (kt + 2 < 128) {
;       const int kn = kt + 2;
; #pragma unroll
;       for (int i = 0; i < 2; ++i) kreg[i] = *(const u32x4*)(kbase + ((size_t)i * SEQ + kn * 64) * 64 + tid * 8);
; #pragma unroll
;       for (int i = 0; i < 2; ++i) {
;         const int cid = tid + NT * i;
;         const int e = cid >> 3, kc = cid & 7;
;         vreg[i] = *(const u32x4*)(vbase + (size_t)e * VTP + kn * 64 + kc * 8);
;       }
;     }
;     __builtin_amdgcn_sched_barrier(0x38F);
;     if (kt >= 0) {
;       const u16* Kc = Ks + (kt & 1) * (256 * 72);
;       const u16* Vc = Kc + 2 * 64 * 72;
;       bf16x8 kf[8];
; #pragma unroll
;       for (int i = 0; i < 8; ++i)
;         kf[i] = *(const bf16x8*)(Kc + (c * 64 + 32 * (i & 1) + li) * 72 + 16 * (i >> 1) + 8 * g);
;       u32x4 vf[16];
; #pragma unroll
;       for (int i = 0; i < 16; ++i) {
;         const int eb = i & 3, s = (i >> 2) & 1, kb = i >> 3;
;         vf[i] = *(const u32x4*)(Vc + (32 * eb + li) * 72 + 32 * kb + 16 * s + 8 * g);
;       }
;       f32x16 S[2];
; #pragma unroll
;       for (int kb = 0; kb < 2; ++kb)
; #pragma unroll
;         for (int r = 0; r < 16; ++r) S[kb][r] = negm;
; #pragma unroll
;       for (int i = 0; i < 8; ++i) S[i & 1] = MFMA(kf[i], qf[i >> 1], S[i & 1]);
;       u32x4 pk[4];
;       float sum = 0.f;
; #pragma unroll
;       for (int ch = 0; ch < 4; ++ch) {
;         const int kb = ch >> 1, s = ch & 1;
; #pragma unroll
;         for (int j2 = 0; j2 < 4; ++j2) {
;           const float p0 = __builtin_amdgcn_exp2f(S[kb][8 * s + 2 * j2]);
.Lat_exit:
	ds_read_b128 v[128:131], v150 offset:0
	ds_read_b128 v[132:135], v150 offset:32
	ds_read_b128 v[136:139], v150 offset:64
	ds_read_b128 v[152:155], v150 offset:96
	ds_read_b128 v[224:227], v150 offset:4608
	ds_read_b128 v[244:247], v150 offset:4640
	global_load_dwordx4 v[232:235], v[148:149], off
	global_load_dwordx4 v[228:231], v[156:157], off
	global_load_dwordx4 v[236:239], v[146:147], off
	global_load_dwordx4 v[240:243], v[144:145], off
	s_waitcnt lgkmcnt(4)
	v_mfma_f32_32x32x16_bf16 v[96:111], v[128:131], v[112:115], v[16:31]
	ds_read_b128 v[128:131], v150 offset:4672
	v_add_f32_e32 v167, v167, v88
	v_add_f32_e32 v190, v190, v89
	v_mfma_f32_32x32x16_bf16 v[96:111], v[132:135], v[116:119], v[96:111]
	ds_read_b128 v[132:135], v150 offset:4704
	v_add_f32_e32 v191, v191, v90
	v_add_f32_e32 v196, v196, v91
	s_waitcnt lgkmcnt(4)
	v_mfma_f32_32x32x16_bf16 v[96:111], v[136:139], v[124:127], v[96:111]
	ds_read_b128 v[136:139], v151 offset:0
	v_add_f32_e32 v167, v167, v92
	v_add_f32_e32 v190, v190, v93
	v_mfma_f32_32x32x16_bf16 v[96:111], v[152:155], v[120:123], v[96:111]
	ds_read_b128 v[152:155], v151 offset:4608
	v_add_f32_e32 v191, v191, v94
	v_add_f32_e32 v196, v196, v95
	v_lshl_add_u64 v[148:149], v[148:149], 0, s[14:15]
	v_lshl_add_u64 v[156:157], v[156:157], 0, s[14:15]
	s_waitcnt lgkmcnt(4)
	v_mfma_f32_32x32x16_bf16 v[80:95], v[224:227], v[112:115], v[16:31]
	ds_read_b128 v[224:227], v151 offset:9216
	v_lshl_add_u64 v[146:147], v[146:147], 0, s[58:59]
	v_lshl_add_u64 v[144:145], v[144:145], 0, s[58:59]
	v_mfma_f32_32x32x16_bf16 v[80:95], v[244:247], v[116:119], v[80:95]
	ds_read_b128 v[244:247], v151 offset:13824
	s_nop 2
	v_exp_f32_e32 v96, v96
	v_exp_f32_e32 v97, v97
	s_waitcnt lgkmcnt(4)
	v_mfma_f32_32x32x16_bf16 v[80:95], v[128:131], v[124:127], v[80:95]
	ds_read_b128 v[128:131], v151 offset:32
	v_exp_f32_e32 v98, v98
	v_exp_f32_e32 v99, v99
	v_exp_f32_e32 v100, v100
	v_mfma_f32_32x32x16_bf16 v[80:95], v[132:135], v[120:123], v[80:95]
	ds_read_b128 v[132:135], v151 offset:4640
	v_exp_f32_e32 v101, v101
	v_exp_f32_e32 v102, v102
	v_exp_f32_e32 v103, v103
	v_add_f32_e32 v167, v167, v96
	v_add_f32_e32 v190, v190, v97
	v_add_f32_e32 v191, v191, v98
	v_cvt_pk_bf16_f32 v176, v96, v97
	v_cvt_pk_bf16_f32 v177, v98, v99
	v_cvt_pk_bf16_f32 v178, v100, v101
	v_cvt_pk_bf16_f32 v179, v102, v103
	v_add_f32_e32 v196, v196, v99
	v_add_f32_e32 v167, v167, v100
	v_add_f32_e32 v190, v190, v101
	v_add_f32_e32 v191, v191, v102
	v_add_f32_e32 v196, v196, v103
	s_waitcnt lgkmcnt(4)
	v_mfma_f32_32x32x16_bf16 v[64:79], v[136:139], v[176:179], v[64:79]
	ds_read_b128 v[136:139], v151 offset:9248
	v_exp_f32_e32 v104, v104
	v_exp_f32_e32 v105, v105
	v_mfma_f32_32x32x16_bf16 v[48:63], v[152:155], v[176:179], v[48:63]
	ds_read_b128 v[152:155], v151 offset:13856
	v_exp_f32_e32 v106, v106
	v_exp_f32_e32 v107, v107
	v_cvt_pk_bf16_f32 v180, v104, v105
	s_waitcnt lgkmcnt(4)
	v_mfma_f32_32x32x16_bf16 v[32:47], v[224:227], v[176:179], v[32:47]
	ds_read_b128 v[224:227], v151 offset:64
	v_exp_f32_e32 v108, v108
	v_exp_f32_e32 v109, v109
	v_cvt_pk_bf16_f32 v181, v106, v107
	v_mfma_f32_32x32x16_bf16 v[0:15], v[244:247], v[176:179], v[0:15]
	ds_read_b128 v[244:247], v151 offset:4672
	v_exp_f32_e32 v110, v110
	v_exp_f32_e32 v111, v111
	v_cvt_pk_bf16_f32 v182, v108, v109
	v_cvt_pk_bf16_f32 v183, v110, v111
	s_nop 0
	s_waitcnt lgkmcnt(4)
	v_mfma_f32_32x32x16_bf16 v[64:79], v[128:131], v[180:183], v[64:79]
	ds_read_b128 v[128:131], v151 offset:9280
	v_exp_f32_e32 v80, v80
	v_exp_f32_e32 v81, v81
	v_mfma_f32_32x32x16_bf16 v[48:63], v[132:135], v[180:183], v[48:63]
	ds_read_b128 v[132:135], v151 offset:13888
	v_exp_f32_e32 v82, v82
	v_exp_f32_e32 v83, v83
	v_cvt_pk_bf16_f32 v184, v80, v81
	s_waitcnt lgkmcnt(4)
	v_mfma_f32_32x32x16_bf16 v[32:47], v[136:139], v[180:183], v[32:47]
	ds_read_b128 v[136:139], v151 offset:96
	v_exp_f32_e32 v84, v84
	v_exp_f32_e32 v85, v85
	v_cvt_pk_bf16_f32 v185, v82, v83
	v_mfma_f32_32x32x16_bf16 v[0:15], v[152:155], v[180:183], v[0:15]
	ds_read_b128 v[152:155], v151 offset:4704
	v_exp_f32_e32 v86, v86
	v_exp_f32_e32 v87, v87
	v_cvt_pk_bf16_f32 v186, v84, v85
	v_cvt_pk_bf16_f32 v187, v86, v87
	s_nop 0
	s_waitcnt lgkmcnt(4)
	v_mfma_f32_32x32x16_bf16 v[64:79], v[224:227], v[184:187], v[64:79]
	ds_read_b128 v[224:227], v151 offset:9312
	v_exp_f32_e32 v88, v88
	v_exp_f32_e32 v89, v89
	v_mfma_f32_32x32x16_bf16 v[48:63], v[244:247], v[184:187], v[48:63]
	ds_read_b128 v[244:247], v151 offset:13920
	v_exp_f32_e32 v90, v90
	v_exp_f32_e32 v91, v91
	v_cvt_pk_bf16_f32 v192, v88, v89
	s_waitcnt lgkmcnt(4)
	v_mfma_f32_32x32x16_bf16 v[32:47], v[128:131], v[184:187], v[32:47]
	v_exp_f32_e32 v92, v92
	v_exp_f32_e32 v93, v93
	v_cvt_pk_bf16_f32 v193, v90, v91
	s_waitcnt vmcnt(0)
	ds_write_b128 v168, v[228:231] offset:36864
	ds_write_b128 v168, v[232:235] offset:46080
	v_mfma_f32_32x32x16_bf16 v[0:15], v[132:135], v[184:187], v[0:15]
	v_exp_f32_e32 v94, v94
	v_exp_f32_e32 v95, v95
	v_cvt_pk_bf16_f32 v194, v92, v93
	v_cvt_pk_bf16_f32 v195, v94, v95
	s_nop 0
	ds_write_b64 v169, v[236:237] offset:55296
	ds_write_b64 v169, v[238:239] offset:55312
	s_waitcnt lgkmcnt(6)
	v_mfma_f32_32x32x16_bf16 v[64:79], v[136:139], v[192:195], v[64:79]
	v_add_f32_e32 v167, v167, v104
	v_add_f32_e32 v190, v190, v105
	v_add_f32_e32 v191, v191, v106
	v_add_f32_e32 v196, v196, v107
	ds_write_b64 v143, v[240:241] offset:55296
	ds_write_b64 v143, v[242:243] offset:55312
	v_mfma_f32_32x32x16_bf16 v[48:63], v[152:155], v[192:195], v[48:63]
	v_add_f32_e32 v167, v167, v108
	v_add_f32_e32 v190, v190, v109
	v_add_f32_e32 v191, v191, v110
	v_add_f32_e32 v196, v196, v111
	s_waitcnt lgkmcnt(6)
	v_mfma_f32_32x32x16_bf16 v[32:47], v[224:227], v[192:195], v[32:47]
	v_add_f32_e32 v167, v167, v80
	v_add_f32_e32 v190, v190, v81
	v_add_f32_e32 v191, v191, v82
	v_add_f32_e32 v196, v196, v83
	v_mfma_f32_32x32x16_bf16 v[0:15], v[244:247], v[192:195], v[0:15]
	v_add_f32_e32 v167, v167, v84
	v_add_f32_e32 v190, v190, v85
	v_add_f32_e32 v191, v191, v86
	v_add_f32_e32 v196, v196, v87
	s_waitcnt lgkmcnt(0)
	s_barrier
; #define MFMA(a, b, c) __builtin_amdgcn_mfma_f32_32x32x16_bf16((a), (b), (c), 0, 0, 0)
; DI void attn_item(const P& p, int l, int item, char* smem) {
;     ...
;     if (kt >= 0) {
;       const u16* Kc = Ks + (kt & 1) * (256 * 72);
;       const u16* Vc = Kc + 2 * 64 * 72;
;       bf16x8 kf[8];
; #pragma unroll
;       for (int i = 0; i < 8; ++i)
;         kf[i] = *(const bf16x8*)(Kc + (c * 64 + 32 * (i & 1) + li) * 72 + 16 * (i >> 1) + 8 * g);
;       u32x4 vf[16];
; #pragma unroll
;       for (int i = 0; i < 16; ++i) {
;         const int eb = i & 3, s = (i >> 2) & 1, kb = i >> 3;
;         vf[i] = *(const u32x4*)(Vc + (32 * eb + li) * 72 + 32 * kb + 16 * s + 8 * g);
;       }
;       f32x16 S[2];
; #pragma unroll
;       for (int kb = 0; kb < 2; ++kb)
; #pragma unroll
;         for (int r = 0; r < 16; ++r) S[kb][r] = negm;
; #pragma unroll
;       for (int i = 0; i < 8; ++i) S[i & 1] = MFMA(kf[i], qf[i >> 1], S[i & 1]);
;       u32x4 pk[4];
;       float sum = 0.f;
; #pragma unroll
;       for (int ch = 0; ch < 4; ++ch) {
;         const int kb = ch >> 1, s = ch & 1;
; #pragma unroll
;         for (int j2 = 0; j2 < 4; ++j2) {
;           const float p0 = __builtin_amdgcn_exp2f(S[kb][8 * s + 2 * j2]);
;           const float p1 = __builtin_amdgcn_exp2f(S[kb][8 * s + 2 * j2 + 1]);
;           sum += p0 + p1;
;           pk[ch][j2] = pack2(p0, p1);
;         }
;       }
;       ls += sum;
; #pragma unroll
;       for (int i = 0; i < 16; ++i) {
;         const int eb = i & 3, ch = i >> 2;
;         O[eb] = MFMA(__builtin_bit_cast(bf16x8, vf[i]), __builtin_bit_cast(bf16x8, pk[ch]), O[eb]);
;       }
;     }
;     __syncthreads();
	ds_read_b128 v[128:131], v150 offset:36864
	ds_read_b128 v[132:135], v150 offset:36896
	ds_read_b128 v[136:139], v150 offset:36928
	ds_read_b128 v[152:155], v150 offset:36960
	ds_read_b128 v[224:227], v150 offset:41472
	ds_read_b128 v[244:247], v150 offset:41504
	s_waitcnt lgkmcnt(4)
	v_mfma_f32_32x32x16_bf16 v[96:111], v[128:131], v[112:115], v[16:31]
	ds_read_b128 v[128:131], v150 offset:41536
	v_add_f32_e32 v167, v167, v88
	v_add_f32_e32 v190, v190, v89
	v_mfma_f32_32x32x16_bf16 v[96:111], v[132:135], v[116:119], v[96:111]
	ds_read_b128 v[132:135], v150 offset:41568
	v_add_f32_e32 v191, v191, v90
	v_add_f32_e32 v196, v196, v91
	s_waitcnt lgkmcnt(4)
	v_mfma_f32_32x32x16_bf16 v[96:111], v[136:139], v[124:127], v[96:111]
	ds_read_b128 v[136:139], v151 offset:36864
	v_add_f32_e32 v167, v167, v92
	v_add_f32_e32 v190, v190, v93
	v_mfma_f32_32x32x16_bf16 v[96:111], v[152:155], v[120:123], v[96:111]
	ds_read_b128 v[152:155], v151 offset:41472
	v_add_f32_e32 v191, v191, v94
	v_add_f32_e32 v196, v196, v95
	s_waitcnt lgkmcnt(4)
	v_mfma_f32_32x32x16_bf16 v[80:95], v[224:227], v[112:115], v[16:31]
	ds_read_b128 v[224:227], v151 offset:46080
	v_mfma_f32_32x32x16_bf16 v[80:95], v[244:247], v[116:119], v[80:95]
	ds_read_b128 v[244:247], v151 offset:50688
	s_nop 6
	v_exp_f32_e32 v96, v96
	v_exp_f32_e32 v97, v97
	s_waitcnt lgkmcnt(4)
	v_mfma_f32_32x32x16_bf16 v[80:95], v[128:131], v[124:127], v[80:95]
	ds_read_b128 v[128:131], v151 offset:36896
	v_exp_f32_e32 v98, v98
	v_exp_f32_e32 v99, v99
	v_exp_f32_e32 v100, v100
	v_mfma_f32_32x32x16_bf16 v[80:95], v[132:135], v[120:123], v[80:95]
	ds_read_b128 v[132:135], v151 offset:41504
	v_exp_f32_e32 v101, v101
	v_exp_f32_e32 v102, v102
	v_exp_f32_e32 v103, v103
	v_add_f32_e32 v167, v167, v96
	v_add_f32_e32 v190, v190, v97
	v_add_f32_e32 v191, v191, v98
	v_cvt_pk_bf16_f32 v176, v96, v97
	v_cvt_pk_bf16_f32 v177, v98, v99
	v_cvt_pk_bf16_f32 v178, v100, v101
	v_cvt_pk_bf16_f32 v179, v102, v103
	v_add_f32_e32 v196, v196, v99
	v_add_f32_e32 v167, v167, v100
	v_add_f32_e32 v190, v190, v101
	v_add_f32_e32 v191, v191, v102
	v_add_f32_e32 v196, v196, v103
	s_waitcnt lgkmcnt(4)
	v_mfma_f32_32x32x16_bf16 v[64:79], v[136:139], v[176:179], v[64:79]
	ds_read_b128 v[136:139], v151 offset:46112
	v_exp_f32_e32 v104, v104
	v_exp_f32_e32 v105, v105
	v_mfma_f32_32x32x16_bf16 v[48:63], v[152:155], v[176:179], v[48:63]
	ds_read_b128 v[152:155], v151 offset:50720
	v_exp_f32_e32 v106, v106
	v_exp_f32_e32 v107, v107
	v_cvt_pk_bf16_f32 v180, v104, v105
	s_waitcnt lgkmcnt(4)
	v_mfma_f32_32x32x16_bf16 v[32:47], v[224:227], v[176:179], v[32:47]
	ds_read_b128 v[224:227], v151 offset:36928
	v_exp_f32_e32 v108, v108
	v_exp_f32_e32 v109, v109
	v_cvt_pk_bf16_f32 v181, v106, v107
	v_mfma_f32_32x32x16_bf16 v[0:15], v[244:247], v[176:179], v[0:15]
	ds_read_b128 v[244:247], v151 offset:41536
	v_exp_f32_e32 v110, v110
	v_exp_f32_e32 v111, v111
	v_cvt_pk_bf16_f32 v182, v108, v109
	v_cvt_pk_bf16_f32 v183, v110, v111
	s_nop 0
	s_waitcnt lgkmcnt(4)
	v_mfma_f32_32x32x16_bf16 v[64:79], v[128:131], v[180:183], v[64:79]
	ds_read_b128 v[128:131], v151 offset:46144
	v_exp_f32_e32 v80, v80
	v_exp_f32_e32 v81, v81
	v_mfma_f32_32x32x16_bf16 v[48:63], v[132:135], v[180:183], v[48:63]
	ds_read_b128 v[132:135], v151 offset:50752
	v_exp_f32_e32 v82, v82
	v_exp_f32_e32 v83, v83
	v_cvt_pk_bf16_f32 v184, v80, v81
	s_waitcnt lgkmcnt(4)
	v_mfma_f32_32x32x16_bf16 v[32:47], v[136:139], v[180:183], v[32:47]
	ds_read_b128 v[136:139], v151 offset:36960
	v_exp_f32_e32 v84, v84
	v_exp_f32_e32 v85, v85
	v_cvt_pk_bf16_f32 v185, v82, v83
	v_mfma_f32_32x32x16_bf16 v[0:15], v[152:155], v[180:183], v[0:15]
	ds_read_b128 v[152:155], v151 offset:41568
	v_exp_f32_e32 v86, v86
	v_exp_f32_e32 v87, v87
	v_cvt_pk_bf16_f32 v186, v84, v85
	v_cvt_pk_bf16_f32 v187, v86, v87
	s_nop 0
	s_waitcnt lgkmcnt(4)
	v_mfma_f32_32x32x16_bf16 v[64:79], v[224:227], v[184:187], v[64:79]
	ds_read_b128 v[224:227], v151 offset:46176
	v_exp_f32_e32 v88, v88
	v_exp_f32_e32 v89, v89
	v_mfma_f32_32x32x16_bf16 v[48:63], v[244:247], v[184:187], v[48:63]
	ds_read_b128 v[244:247], v151 offset:50784
	v_exp_f32_e32 v90, v90
	v_exp_f32_e32 v91, v91
	v_cvt_pk_bf16_f32 v192, v88, v89
	s_waitcnt lgkmcnt(4)
	v_mfma_f32_32x32x16_bf16 v[32:47], v[128:131], v[184:187], v[32:47]
	v_exp_f32_e32 v92, v92
	v_exp_f32_e32 v93, v93
	v_cvt_pk_bf16_f32 v193, v90, v91
	v_mfma_f32_32x32x16_bf16 v[0:15], v[132:135], v[184:187], v[0:15]
	v_exp_f32_e32 v94, v94
	v_exp_f32_e32 v95, v95
	v_cvt_pk_bf16_f32 v194, v92, v93
	v_cvt_pk_bf16_f32 v195, v94, v95
	s_nop 0
	s_waitcnt lgkmcnt(2)
	v_mfma_f32_32x32x16_bf16 v[64:79], v[136:139], v[192:195], v[64:79]
	v_add_f32_e32 v167, v167, v104
	v_add_f32_e32 v190, v190, v105
	v_add_f32_e32 v191, v191, v106
	v_add_f32_e32 v196, v196, v107
	v_mfma_f32_32x32x16_bf16 v[48:63], v[152:155], v[192:195], v[48:63]
	v_add_f32_e32 v167, v167, v108
	v_add_f32_e32 v190, v190, v109
	v_add_f32_e32 v191, v191, v110
	v_add_f32_e32 v196, v196, v111
	s_waitcnt lgkmcnt(0)
	v_mfma_f32_32x32x16_bf16 v[32:47], v[224:227], v[192:195], v[32:47]
	v_add_f32_e32 v167, v167, v80
	v_add_f32_e32 v190, v190, v81
	v_add_f32_e32 v191, v191, v82
	v_add_f32_e32 v196, v196, v83
	v_mfma_f32_32x32x16_bf16 v[0:15], v[244:247], v[192:195], v[0:15]
	v_add_f32_e32 v167, v167, v84
	v_add_f32_e32 v190, v190, v85
	v_add_f32_e32 v191, v191, v86
	v_add_f32_e32 v196, v196, v87
	s_waitcnt lgkmcnt(0)
	s_barrier
; #define MFMA(a, b, c) __builtin_amdgcn_mfma_f32_32x32x16_bf16((a), (b), (c), 0, 0, 0)
; DI void attn_item(const P& p, int l, int item, char* smem) {
;     ...
;       ls += sum;
; #pragma unroll
;       for (int i = 0; i < 16; ++i) {
;         const int eb = i & 3, ch = i >> 2;
;         O[eb] = MFMA(__builtin_bit_cast(bf16x8, vf[i]), __builtin_bit_cast(bf16x8, pk[ch]), O[eb]);
;       }
;     }
;     __syncthreads();
;   }
;   const float lt = ls + __shfl_xor(ls, 32);
;   const float inv = (c == 0) ? (1.0f / lt) : (lam / lt);
;   float* exch = (float*)smem + qg * (64 * 64);
;   if (c == 1) {
; #pragma unroll
;     for (int eb = 0; eb < 4; ++eb)
; #pragma unroll
;       for (int r = 0; r < 16; ++r) exch[(eb * 16 + r) * 64 + lane] = O[eb][r] * inv;
;   }
;   __syncthreads();
;   if (c == 0) {
;     float ss = 0.f;
; #pragma unroll
;     for (int eb = 0; eb < 4; ++eb)
; #pragma unroll
;       for (int r = 0; r < 16; ++r) {
;         const float o = O[eb][r] * inv - exch[(eb * 16 + r) * 64 + lane];
;         O[eb][r] = o;
;         ss += o * o;
;       }
;     ss += __shfl_xor(ss, 32);
;     const float rn = rsqrtf(ss * (1.0f / 128.0f) + 1e-5f) * (1.0f - lam_init);
;     const size_t tok = (size_t)b * SEQ + tq;
; #pragma unroll
;     for (int eb = 0; eb < 4; ++eb)
; #pragma unroll
;       for (int rq = 0; rq < 4; ++rq) {
;         const int e = 32 * eb + 8 * rq + 4 * g;
;         const uint2 gt = *(const uint2*)(p.AG + tok * 512 + h * 128 + e);
;         const float4 sg = *(const float4*)(p.subg + l * 128 + e);
	v_add_f32_e32 v167, v167, v88
	v_add_f32_e32 v190, v190, v89
	v_add_f32_e32 v191, v191, v90
	v_add_f32_e32 v196, v196, v91
	v_add_f32_e32 v167, v167, v92
	v_add_f32_e32 v190, v190, v93
	v_add_f32_e32 v191, v191, v94
	v_add_f32_e32 v196, v196, v95
	v_add_f32_e32 v167, v167, v190
	v_add_f32_e32 v191, v191, v196
	v_readlane_b32 s6, v248, 5
	v_add_f32_e32 v96, v165, v166
	v_add_f32_e32 v97, v163, v164
	v_mul_f32_e32 v96, 0x3fb8aa3b, v96
	v_mul_f32_e32 v97, 0x3fb8aa3b, v97
	v_exp_f32_e32 v139, v96
	v_exp_f32_e32 v17, v97
	v_add_f32_e32 v16, v167, v191
	ds_bpermute_b32 v18, v158, v16
	v_sub_f32_e32 v17, v17, v139
	v_add_f32_e32 v17, s6, v17
	s_movk_i32 s6, 0x100
	v_cmp_gt_u32_e64 s[6:7], s6, v161
	s_waitcnt lgkmcnt(0)
	v_add_f32_e32 v16, v16, v18
	s_nop 0
	v_cndmask_b32_e64 v17, v17, 1.0, s[6:7]
	v_div_scale_f32 v18, s[10:11], v16, v16, v17
	v_rcp_f32_e32 v19, v18
	s_nop 0
	v_fma_f32 v24, -v18, v19, 1.0
	s_nop 0
	v_fmac_f32_e32 v19, v24, v19
	v_div_scale_f32 v24, vcc, v17, v16, v17
	v_mul_f32_e32 v25, v24, v19
	v_fma_f32 v26, -v18, v25, v24
	v_fmac_f32_e32 v25, v26, v19
	v_fma_f32 v18, -v18, v25, v24
	s_nop 0
	v_div_fmas_f32 v18, v18, v19, v25
	v_div_fixup_f32 v80, v18, v16, v17
	v_lshl_add_u32 v16, v162, 14, 0
	v_cmp_eq_u32_e32 vcc, 1, v160
	v_lshl_add_u32 v18, v141, 2, v16
	s_nop 0
	s_and_saveexec_b64 s[10:11], s[6:7]
	s_cbranch_execz .Lfin_nl
	v_and_b32_e32 v142, 15, v161
	v_bfe_u32 v143, v161, 4, 2
	v_and_b32_e32 v144, 0xffffffe0, v140
	v_add_u32_e32 v144, v144, v143
	s_lshl_b32 s56, s12, 11
	s_and_b32 s56, s56, 0x2000
	v_add_u32_e32 v144, s56, v144
	v_lshlrev_b32_e32 v144, 10, v144
	s_lshl_b32 s56, s95, 8
	s_and_b32 s56, s56, 0x300
	v_add_u32_e32 v144, s56, v144
	v_lshl_add_u32 v144, v142, 4, v144
	v_mov_b32_e32 v147, v144
	v_lshlrev_b32_e32 v145, 5, v142
	global_load_dwordx4 v[100:103], v145, s[30:31]
	global_load_dwordx4 v[104:107], v145, s[30:31] offset:16
	global_load_dwordx4 v[228:231], v144, s[44:45]
	v_add_u32_e32 v144, 0x1000, v144
	global_load_dwordx4 v[232:235], v144, s[44:45]
	v_add_u32_e32 v144, 0x1000, v144
	global_load_dwordx4 v[236:239], v144, s[44:45]
	v_add_u32_e32 v144, 0x1000, v144
	global_load_dwordx4 v[240:243], v144, s[44:45]
	v_add_u32_e32 v144, 0x1000, v144
	global_load_dwordx4 v[84:87], v144, s[44:45]
	v_add_u32_e32 v144, 0x1000, v144
	global_load_dwordx4 v[88:91], v144, s[44:45]
	v_add_u32_e32 v144, 0x1000, v144
	global_load_dwordx4 v[92:95], v144, s[44:45]
	v_add_u32_e32 v144, 0x1000, v144
	global_load_dwordx4 v[96:99], v144, s[44:45]
